# placement-checked XCD-local barriers (runtime group census with global-barrier fallback) after D/OUT GEMMs; L1 invalidate at arrival; no coop grid.sync
# speedup vs baseline: 1.0053x; 1.0053x over previous
; #define LAS __attribute__((address_space(3)))
; __global__ void __launch_bounds__(NTHR, 2) mega_fwd(Args a) {
;     extern __shared__ __attribute__((aligned(16))) unsigned char lds_raw[];
;     LAS unsigned char* lds = (LAS unsigned char*)lds_raw;
;     cg::grid_group grid = cg::this_grid();
;     const int G = gridDim.x, bx = blockIdx.x, NGW = G * NWAVES;
;     bf16* XB = (bf16*)(a.ws + WS_XB); bf16* HB = (bf16*)(a.ws + WS_H); bf16* PROJ = (bf16*)(a.ws + WS_PROJ); bf16* Y = (bf16*)(a.ws + WS_Y);
;     float* SS = (float*)(a.ws + WS_SS);
;     grid.sync();
;     if (threadIdx.x < 2) ((volatile LAS unsigned*)(lds + 131072))[threadIdx.x] = 0u;
;     for (int i = threadIdx.x; i < 8 * 384; i += NTHR) {
;         const int hh = i / 384, rel = i % 384 - 192, n = rel < 0 ? -rel : rel; int bk = rel > 0 ? 16 : 0;
;         if (n < 8) bk += n; else { int k = 8 + (31 - __builtin_clz(n * n)) - 6; bk += k < 15 ? k : 15; }
;         ((LAS float*)(lds + LDS_BTAB))[i] = n <= 128 ? a.in[15][bk * 8 + hh] * 1.4426950408889634f : -1e30f; }
_Z8mega_fwd4Args:
	s_load_dword s3, s[0:1], 0xe0
	s_load_dwordx2 s[94:95], s[0:1], 0xd8
	s_load_dwordx16 s[4:19], s[0:1], 0x0
	s_load_dwordx4 s[48:51], s[0:1], 0xc0
	v_and_b32_e32 v226, 0x3ff, v0
	v_cmp_gt_u32_e32 vcc, 4, v226
	v_lshl_add_u32 v0, v226, 2, 0
	s_waitcnt lgkmcnt(0)
	v_writelane_b32 v252, s4, 0
	s_barrier
	s_nop 0
	v_writelane_b32 v252, s5, 1
	v_writelane_b32 v252, s6, 2
	v_writelane_b32 v252, s7, 3
	v_writelane_b32 v252, s8, 4
	v_writelane_b32 v252, s9, 5
	v_writelane_b32 v252, s10, 6
	v_writelane_b32 v252, s11, 7
	v_writelane_b32 v252, s12, 8
	v_writelane_b32 v252, s13, 9
	v_writelane_b32 v252, s14, 10
	v_writelane_b32 v252, s15, 11
	v_writelane_b32 v252, s16, 12
	v_writelane_b32 v252, s17, 13
	v_writelane_b32 v252, s18, 14
	v_writelane_b32 v252, s19, 15
	s_load_dwordx16 s[4:19], s[0:1], 0x40
	s_waitcnt lgkmcnt(0)
	v_writelane_b32 v252, s4, 16
	s_nop 1
	v_writelane_b32 v252, s5, 17
	v_writelane_b32 v252, s6, 18
	v_writelane_b32 v252, s7, 19
	v_writelane_b32 v252, s8, 20
	v_writelane_b32 v252, s9, 21
	v_writelane_b32 v252, s10, 22
	v_writelane_b32 v252, s11, 23
	v_writelane_b32 v252, s12, 24
	v_writelane_b32 v252, s13, 25
	v_writelane_b32 v252, s14, 26
	v_writelane_b32 v252, s15, 27
	v_writelane_b32 v252, s16, 28
	v_writelane_b32 v252, s17, 29
	v_writelane_b32 v252, s18, 30
	v_writelane_b32 v252, s19, 31
	s_load_dwordx16 s[4:19], s[0:1], 0x80
	s_waitcnt lgkmcnt(0)
	v_writelane_b32 v252, s4, 32
	s_nop 1
	v_writelane_b32 v252, s5, 33
	v_writelane_b32 v252, s6, 34
	v_writelane_b32 v252, s7, 35
	v_writelane_b32 v252, s8, 36
	v_writelane_b32 v252, s9, 37
	v_writelane_b32 v252, s10, 38
	v_writelane_b32 v252, s11, 39
	v_writelane_b32 v252, s12, 40
	v_writelane_b32 v252, s13, 41
	v_writelane_b32 v252, s14, 42
	v_writelane_b32 v252, s15, 43
	v_writelane_b32 v252, s16, 44
	v_writelane_b32 v252, s17, 45
	v_writelane_b32 v252, s18, 46
	v_writelane_b32 v252, s19, 47
	s_and_saveexec_b64 s[0:1], vcc
	v_add_u32_e32 v1, 0x20000, v0
	v_mov_b32_e32 v2, 0
	ds_write_b32 v1, v2
	s_or_b64 exec, exec, s[0:1]
	v_add_u32_e32 v0, 0x21100, v0
	s_mov_b64 s[0:1], 0
	s_mov_b32 s6, 0xffff
	s_mov_b32 s7, 0xaaab
	s_movk_i32 s24, 0x180
	s_movk_i32 s25, 0xc0
	s_movk_i32 s26, 0x81
	s_movk_i32 s27, 0x9ff
	v_mov_b32_e32 v1, v226
	s_branch .LBB0_14

; #define LAS __attribute__((address_space(3)))
; __device__ __forceinline__ unsigned xb_add(unsigned* p, unsigned v) { return __hip_atomic_fetch_add(p, v, __ATOMIC_RELAXED, __HIP_MEMORY_SCOPE_AGENT); }
; __device__ __forceinline__ unsigned xb_xcc_id() { return (unsigned)__builtin_amdgcn_s_getreg((3 << 11) | 20) & 0xFu; }
; __device__ __forceinline__ XcdBarrier xcd_barrier_post(unsigned* bar, volatile LAS unsigned* st) {
;     XcdBarrier b; b.bar = bar; b.x = xb_xcc_id(); b.st = st;
;     if (threadIdx.x == 0) (void)xb_add(&bar[XB_XCNT(b.x)], 1u);
;     return b;
; }
; __global__ void __launch_bounds__(NTHR, 2) mega_fwd(Args a) {
;     ...
;     __syncthreads();
;     const XcdBarrier xbar = xcd_barrier_post((unsigned*)a.ws, (volatile LAS unsigned*)(lds + 131072));
.LBB0_20:
	s_or_b64 exec, exec, s[0:1]
	s_waitcnt lgkmcnt(0)
	s_barrier
	s_getreg_b32 s0, hwreg(HW_REG_XCC_ID, 0, 4)
	s_and_b32 s33, s0, 15
	v_cmp_eq_u32_e64 s[80:81], 0, v226
	s_and_saveexec_b64 s[0:1], s[80:81]
	s_cbranch_execz .LBB0_23
	s_mov_b64 s[4:5], exec
	v_mbcnt_lo_u32_b32 v0, s4, 0
	v_mbcnt_hi_u32_b32 v0, s5, v0
	v_cmp_eq_u32_e32 vcc, 0, v0
	s_and_b64 s[6:7], exec, vcc
	s_mov_b64 exec, s[6:7]
	s_cbranch_execz .LBB0_23
	s_lshl_b32 s6, s33, 8
	s_bcnt1_i32_b64 s4, s[4:5]
	v_mov_b32_e32 v0, s6
	v_mov_b32_e32 v1, s4
	global_atomic_add v0, v1, s[50:51] offset:1024
	s_and_b32 s6, s2, 7
	s_lshl_b32 s6, s6, 8
	s_add_i32 s6, s6, 0x3600
	s_lshl_b32 s4, 1, s33
	v_mov_b32_e32 v0, s6
	v_mov_b32_e32 v1, s4
	global_atomic_or v0, v1, s[50:51]

; #define GSYNC() do { _Pragma("unroll 1") for (int sy_ = 0; sy_ < PROBE_SYNCREP; ++sy_) xcd_barrier(xbar); } while (0)
; __global__ void __launch_bounds__(NTHR, 2) mega_fwd(Args a) {
;     ...
;     GSYNC();
;     for (int l = 0; l < DEPTH; ++l) {
;         const bf16* wl = (const bf16*)(a.ws + WS_W) + (size_t)l * W_LAYER;
; #pragma unroll 1
;         for (int f = 0; f < 2; ++f) {
;             if (f == 1) {
;                 { pg8::Gemm g{XB, wl + W_IN, T, DIN, D}; pg8::StaticOrder S; S.init(T, DIN, G, bx); pg8::EpiProj E{PROJ, SS};
.LBB0_100:
	s_or_b64 exec, exec, s[0:1]
	s_and_saveexec_b64 s[0:1], s[80:81]
	s_cbranch_execz .Lgrp_done
	s_and_b32 s24, s2, 7
	s_lshl_b32 s24, s24, 8
	s_add_i32 s24, s24, 0x3600
	v_mov_b32_e32 v0, s24
	global_load_dword v1, v0, s[50:51] sc1
	v_readlane_b32 s25, v253, 20
	s_sub_u32 s25, s25, s50
	s_sub_u32 s25, s25, 0x1400
	s_lshr_b32 s25, s25, 8
	s_lshl_b32 s25, 1, s25
	v_mov_b32_e32 v2, s25
	s_waitcnt vmcnt(0)
	v_cmp_ne_u32_e32 vcc, v1, v2
	s_and_saveexec_b64 s[26:27], vcc
	s_cbranch_execz .Lgrp_ok
	v_mov_b32_e32 v0, 0x3e00
	v_mov_b32_e32 v1, 1
	global_atomic_or v0, v1, s[50:51]
.Lgrp_ok:
	s_or_b64 exec, exec, s[26:27]
.Lgrp_done:
	s_or_b64 exec, exec, s[0:1]
	s_add_u32 s24, s50, 0xc000000
	s_addc_u32 s25, s51, 0
	s_add_u32 s10, s50, 0xf800000
	s_addc_u32 s11, s51, 0
	s_add_u32 s0, s50, 0x100000
	s_addc_u32 s1, s51, 0
	v_writelane_b32 v253, s0, 28
	s_cmpk_lt_i32 s2, 0x1c0
	s_mov_b32 s89, 0
	v_writelane_b32 v253, s1, 29
	s_cselect_b64 s[0:1], -1, 0
	v_writelane_b32 v253, s0, 30
	s_ashr_i32 s3, s2, 31
	s_ashr_i32 s33, s94, 31
	v_writelane_b32 v253, s1, 31
	s_lshr_b32 s0, s3, 29
	s_add_i32 s0, s2, s0
	s_ashr_i32 s30, s0, 3
	s_and_b32 s0, s0, -8
	s_sub_i32 s31, s2, s0
	s_cmpk_lt_i32 s2, 0x300
	s_cselect_b64 s[0:1], -1, 0
	s_add_u32 s72, s50, 0x11f00000
	s_addc_u32 s73, s51, 0
	v_writelane_b32 v253, s0, 32
	s_add_u32 s74, s50, 0x11900000
	s_addc_u32 s75, s51, 0
	v_writelane_b32 v253, s1, 33
	s_lshl_b32 s0, s2, 9
	v_writelane_b32 v253, s0, 34
	s_add_u32 s0, s50, 0x11d00000
	s_addc_u32 s1, s51, 0
	v_writelane_b32 v253, s0, 35
	s_cmpk_lt_i32 s2, 0x100
	s_waitcnt lgkmcnt(0)
	v_writelane_b32 v253, s1, 36
	s_cselect_b64 s[0:1], -1, 0
	v_writelane_b32 v253, s0, 37
	s_barrier
;     __host__ __device__ bool next(int i, Unit& u) const {
;         const long L = (long)i * G + c; if (L >= nwg) return false;
;         int wgid = (int)L; { const int q = nwg / NXCD, r = nwg % NXCD, xcd = wgid % NXCD, off = wgid / NXCD; wgid = (xcd < r ? xcd * (q + 1) : r * (q + 1) + (xcd - r) * q) + off; }
;         const int nig = WGM * nN, gid = wgid / nig, fm = gid * WGM, gsz = (nM - fm) < WGM ? (nM - fm) : WGM;
;         u.pm = fm + ((wgid % nig) % gsz); u.pn = (wgid % nig) / gsz; return true;
;     }
; __global__ void __launch_bounds__(NTHR, 2) mega_fwd(Args a) {
;     ...
;             { pg8::Gemm g{XB, wl + (f ? W_GU2 : W_GU1), T, NGU, D}; pg8::StaticOrder S; S.init(T, NGU, G, bx); pg8::EpiSwiglu E{HB, SS};
;               pg8::gemm_phase<pg8::EpiSwiglu, pg8::StaticOrder, true, true>(lds, g, S, E); }
;             { const int first = ((T / 256) * (NGU / 256)) % G, nidle = G - first;
;               const int cl = f ? l + 1 : l, lo = f ? 0 : (l == 0 ? 2 * I_G : PER / 2), hi = f ? PER / 2 : PER;
;               if (cl < DEPTH && bx >= first) { int tid_ = threadIdx.x; asm volatile("" : "+v"(tid_)); const int lane = tid_ & 63, wave = __builtin_amdgcn_readfirstlane(tid_ >> 6);
;                   constexpr int D2_LO = 2 * (2 * I_G + I_D) + I_IN + I_OUT - I_D, D2_HI = D2_LO + I_D;
;                   const int gwt = (bx - first) * NWAVES + wave, ngt = nidle * NWAVES;
;                   if (l == 0 && f == 0) { convert_items(a, lds, 0, lo, D2_LO, gwt, ngt, wave, lane); convert_items(a, lds, 0, D2_HI, PER, gwt, ngt, wave, lane); }
	s_nop 0
	v_writelane_b32 v253, s1, 38
	s_lshl_b32 s0, s31, 5
	s_cmpk_lt_i32 s2, 0x580
	s_cselect_b64 s[4:5], -1, 0
	v_writelane_b32 v253, s4, 39
	s_mul_i32 s1, s31, 33
	v_lshlrev_b32_e32 v228, 4, v226
	v_writelane_b32 v253, s5, 40
	s_add_u32 s4, s50, 0x2200000
	s_addc_u32 s5, s51, 0
	v_writelane_b32 v253, s4, 41
	s_mov_b32 s70, 0x10000
	s_waitcnt vmcnt(4)
	v_mov_b32_e32 v1, 0
	v_writelane_b32 v253, s5, 42
	s_add_u32 s4, s50, 0x1700000
	s_addc_u32 s5, s51, 0
	v_writelane_b32 v253, s4, 43
	s_mov_b32 s71, 0x16000
	v_mov_b32_e32 v229, 0x358637bd
	v_writelane_b32 v253, s5, 44
	s_add_u32 s4, s50, 0x1500000
	s_addc_u32 s5, s51, 0
	v_writelane_b32 v253, s4, 45
	v_mov_b32_e32 v230, 1
	v_mov_b32_e32 v231, 0x3ecc95a3
	v_writelane_b32 v253, s5, 46
	s_add_u32 s4, s50, 0x1180000
	s_addc_u32 s5, s51, 0
	v_writelane_b32 v253, s4, 47
	v_mbcnt_hi_u32_b32 v227, -1, v58
	v_mov_b32_e32 v190, 0x3f317218
	v_writelane_b32 v253, s5, 48
	s_add_u32 s4, s50, 0xc00000
	s_addc_u32 s5, s51, 0
	v_writelane_b32 v253, s4, 49
	v_mov_b32_e32 v232, 0x7f800000
	v_mov_b32_e32 v233, 0x7fc00000
	v_writelane_b32 v253, s5, 50
	s_add_u32 s4, s50, 0x2780000
	s_addc_u32 s5, s51, 0
	s_cmp_lt_i32 s31, 0
	s_cselect_b32 s28, 57, 56
	s_mul_i32 s28, s31, s28
	s_cselect_b32 s34, s1, s0
	s_movk_i32 s0, 0xb1
	s_cselect_b32 s35, s0, 0xb0
	s_add_i32 s28, s28, s30
	s_mul_hi_i32 s0, s28, 0x92492493
	s_add_i32 s0, s0, s28
	s_lshr_b32 s1, s0, 31
	s_ashr_i32 s0, s0, 5
	s_add_i32 s0, s0, s1
	s_mul_i32 s1, s0, 56
	s_sub_i32 s1, s28, s1
	s_lshl_b32 s29, s0, 3
	s_bfe_i32 s0, s1, 0x80000
	s_bfe_u32 s0, s0, 0x3000c
	s_add_i32 s28, s1, s0
	s_bfe_i32 s0, s28, 0x80000
	s_and_b32 s28, s28, 0xf8
	s_sub_i32 s1, s1, s28
	v_writelane_b32 v253, s4, 51
	s_sext_i32_i16 s36, s0
	s_sext_i32_i8 s1, s1
	v_writelane_b32 v253, s5, 52
	s_add_i32 s6, s29, s1
	s_ashr_i32 s1, s36, 3
	s_lshr_b32 s0, s36, 3
	v_writelane_b32 v253, s1, 53
	s_mov_b32 s4, s6
	v_writelane_b32 v253, s4, 54
	s_bfe_i64 s[0:1], s[0:1], 0x100000
	s_ashr_i32 s7, s6, 31
	v_writelane_b32 v253, s5, 55
	s_lshl_b64 s[0:1], s[0:1], 19
	s_lshl_b64 s[28:29], s[6:7], 19
	v_writelane_b32 v253, s0, 56
	v_mov_b32_e32 v234, 0xff800000
	v_mov_b32_e32 v192, 0xc138aa3b
	v_writelane_b32 v253, s1, 57
	s_add_u32 s0, s22, s28
	s_addc_u32 s1, s23, s29
	s_add_u32 s4, s0, 0x40000
	v_writelane_b32 v253, s0, 58
	s_addc_u32 s5, s1, 0
	v_mov_b32_e32 v235, 0xe00
	v_writelane_b32 v253, s1, 59
	s_add_i32 s0, s34, s30
	s_ashr_i32 s1, s0, 31
	s_lshr_b32 s1, s1, 27
	s_add_i32 s1, s0, s1
	s_ashr_i32 s28, s1, 5
	s_and_b32 s1, s1, 0xffe0
	s_sub_i32 s1, s0, s1
	s_bfe_i32 s0, s1, 0x80000
	s_bfe_u32 s0, s0, 0x3000c
	s_add_i32 s29, s1, s0
	s_bfe_i32 s0, s29, 0x80000
	s_and_b32 s29, s29, 0xf8
	s_sub_i32 s1, s1, s29
	v_writelane_b32 v253, s4, 60
	s_lshl_b32 s28, s28, 3
	s_sext_i32_i16 s34, s0
	s_sext_i32_i8 s1, s1
	v_writelane_b32 v253, s5, 61
	s_add_i32 s6, s28, s1
	s_ashr_i32 s1, s34, 3
	v_writelane_b32 v253, s1, 62
	s_mul_i32 s1, s31, s35
	s_add_i32 s1, s1, s30
	s_mul_hi_i32 s28, s1, 0x2e8ba2e9
	s_lshr_b32 s29, s28, 31
	s_ashr_i32 s28, s28, 5
	s_add_i32 s28, s28, s29
	s_lshl_b32 s29, s28, 3
	s_mulk_i32 s28, 0xb0
	s_sub_i32 s1, s1, s28
	s_bfe_u32 s28, s1, 0x3001c
	s_add_i32 s30, s1, s28
	s_sext_i32_i16 s31, s30
	s_and_b32 s30, s30, 0xfff8
	s_sub_i32 s1, s1, s30
	s_sext_i32_i16 s1, s1
	s_add_i32 s8, s29, s1
	s_lshr_b32 s28, s31, 3
	s_mov_b32 s4, s8
	v_writelane_b32 v254, s4, 0
	s_bfe_i64 s[28:29], s[28:29], 0x100000
	s_ashr_i32 s9, s8, 31
	v_writelane_b32 v254, s5, 1
	s_lshl_b64 s[4:5], s[28:29], 19
	s_lshr_b32 s0, s34, 3
	s_ashr_i32 s1, s31, 3
	s_lshl_b64 s[30:31], s[8:9], 19
	v_writelane_b32 v254, s4, 2
	v_writelane_b32 v253, s1, 63
	v_mov_b32_e32 v236, 0xfff
	v_writelane_b32 v254, s5, 3
	s_add_u32 s4, s22, s30
	s_addc_u32 s5, s23, s31
	s_add_u32 s8, s4, 0x40000
	v_writelane_b32 v254, s4, 4
	s_addc_u32 s9, s5, 0
	s_bfe_i64 s[0:1], s[0:1], 0x100000
	v_writelane_b32 v254, s5, 5
	v_writelane_b32 v254, s8, 6
	s_lshl_b64 s[0:1], s[0:1], 19
	s_ashr_i32 s7, s6, 31
	v_writelane_b32 v254, s9, 7
	v_writelane_b32 v254, s0, 8
	s_lshl_b64 s[28:29], s[6:7], 19
	v_mov_b64_e32 v[194:195], 0x100
	v_writelane_b32 v254, s1, 9
	s_add_u32 s0, s10, s28
	v_writelane_b32 v254, s10, 10
	s_addc_u32 s1, s11, s29
	s_add_u32 s4, s0, 0x40000
	v_writelane_b32 v254, s11, 11
	v_writelane_b32 v254, s0, 12
	s_addc_u32 s5, s1, 0
	v_mov_b64_e32 v[196:197], 0xff
	v_writelane_b32 v254, s1, 13
	v_writelane_b32 v254, s4, 14
	s_mul_i32 s1, s6, 0x160000
	s_mul_hi_i32 s0, s6, 0x160000
	v_writelane_b32 v254, s5, 15
	s_mov_b32 s4, s6
	v_writelane_b32 v254, s4, 16
	v_mov_b64_e32 v[198:199], 0x57f
	s_movk_i32 s31, 0xe00
	v_writelane_b32 v254, s5, 17
	s_add_u32 s4, s24, s1
	s_addc_u32 s5, s25, s0
	s_add_u32 s0, s4, 0xb0000
	v_writelane_b32 v254, s4, 18
	s_addc_u32 s1, s5, 0
	s_mov_b32 s90, 0xb000
	v_writelane_b32 v254, s5, 19
	v_writelane_b32 v254, s0, 20
	s_movk_i32 s91, 0x7fff
	s_mov_b32 s34, 0xf149f2ca
	v_writelane_b32 v254, s1, 21
	s_abs_i32 s0, s94
	v_cvt_f32_u32_e32 v0, s0
	s_movk_i32 s1, 0x100
	v_cmp_gt_u32_e64 s[36:37], s1, v226
	s_sub_i32 s1, 0, s0
	v_rcp_iflag_f32_e32 v0, v0
	s_mov_b32 s35, 0xffff0000
	s_brev_b32 s56, 64
	s_brev_b32 s57, 48
	v_mul_f32_e32 v0, 0x4f7ffffe, v0
	v_cvt_u32_f32_e32 v0, v0
	s_movk_i32 s58, 0x1600
	s_mov_b64 s[52:53], 0x80
	s_mov_b64 s[54:55], 0x2000000
	v_readfirstlane_b32 s28, v0
	s_mul_i32 s1, s1, s28
	s_mul_hi_u32 s1, s28, s1
	s_add_i32 s28, s28, s1
	s_mul_hi_u32 s1, s28, 0x580
	s_mul_i32 s1, s1, s0
	s_sub_i32 s1, 0x580, s1
	s_sub_i32 s28, s1, s0
	s_cmp_ge_u32 s1, s0
	s_cselect_b32 s1, s28, s1
	s_sub_i32 s28, s1, s0
	s_cmp_ge_u32 s1, s0
	s_cselect_b32 s0, s28, s1
	s_cmp_lt_i32 s2, s0
	s_cselect_b64 s[4:5], -1, 0
	v_writelane_b32 v254, s4, 22
	s_sub_i32 s1, s94, s0
	s_sub_i32 s0, s2, s0
	v_writelane_b32 v254, s5, 23
	s_lshl_b32 s0, s0, 3
	v_writelane_b32 v254, s0, 24
	s_lshl_b32 s0, s2, 6
	v_writelane_b32 v254, s0, 25
	s_lshl_b32 s0, s94, 6
	v_writelane_b32 v254, s0, 26
	s_add_i32 s0, 0, 0x20000
	v_writelane_b32 v254, s0, 27
	s_add_i32 s0, 0, 0x20004
	v_writelane_b32 v254, s0, 28
	v_writelane_b32 v254, s82, 29
	s_lshl_b32 s30, s1, 3
	s_mov_b32 s28, s89
	v_writelane_b32 v254, s83, 30
	v_writelane_b32 v254, s68, 31
	s_nop 1
	v_writelane_b32 v254, s69, 32
	v_writelane_b32 v254, s72, 33
	s_nop 1
	v_writelane_b32 v254, s73, 34
	v_writelane_b32 v254, s74, 35
	s_nop 1
	v_writelane_b32 v254, s75, 36
	s_branch .LBB0_102

; __device__ __forceinline__ unsigned xb_ld(unsigned* p)              { return __hip_atomic_load(p, __ATOMIC_RELAXED, __HIP_MEMORY_SCOPE_AGENT); }
; __device__ __forceinline__ unsigned xb_add(unsigned* p, unsigned v) { return __hip_atomic_fetch_add(p, v, __ATOMIC_RELAXED, __HIP_MEMORY_SCOPE_AGENT); }
; #define XB_SPIN(cond, bar) do { unsigned _sp = 0; while (cond) { __builtin_amdgcn_s_sleep(1); \
;     if ((++_sp & 255u) == 0u) { if (xb_ld(&(bar)[XB_TMO])) break; if (_sp > XB_SPIN_CAP) { atomicAdd(&(bar)[XB_TMO], 1u); break; } } } } while (0)
; #define GSYNC() do { _Pragma("unroll 1") for (int sy_ = 0; sy_ < PROBE_SYNCREP; ++sy_) xcd_barrier(xbar); } while (0)
; __device__ __forceinline__ void xcd_barrier(const XcdBarrier& b) {
;     asm volatile("s_waitcnt vmcnt(0)" ::: "memory");
;     __syncthreads();
;     if (threadIdx.x == 0) {
;         unsigned* bar = b.bar;
;         __builtin_amdgcn_s_waitcnt(0);
;         unsigned nloc = b.st[0], nx = b.st[1];
;         if (nloc == 0u) { xcd_barrier_complete(bar, b.x, nloc, nx); b.st[0] = nloc; b.st[1] = nx; }
;         const unsigned old = xb_add(&bar[XB_XSUB(b.x)], 1u);
;         const unsigned gen = old / nloc;
;         if (old + 1u == (gen + 1u) * nloc) {
;             __builtin_amdgcn_fence(__ATOMIC_RELEASE, "agent");
;             asm volatile("s_waitcnt vmcnt(0)" ::: "memory");
;             const unsigned og = xb_add(&bar[XB_TOP], 1u);
;             const unsigned tg = og / nx;
;             if (og + 1u == (tg + 1u) * nx) xb_add(&bar[XB_TOPGEN], 1u);
;             else XB_SPIN(xb_ld(&bar[XB_TOPGEN]) == tg, bar);
;             __builtin_amdgcn_fence(__ATOMIC_ACQUIRE, "agent");
;             xb_add(&bar[XB_XGEN(b.x)], 1u);
;             asm volatile("s_waitcnt vmcnt(0)" ::: "memory");
;         } else {
;             XB_SPIN(xb_ld(&bar[XB_XGEN(b.x)]) == gen, bar);
;             __builtin_amdgcn_fence(__ATOMIC_ACQUIRE, "agent");
;             asm volatile("s_waitcnt vmcnt(0)" ::: "memory");
;         }
;     }
;     __syncthreads();
; }
; __global__ void __launch_bounds__(NTHR, 2) mega_fwd(Args a) {
;     ...
;                 GSYNC();
.LBB0_435:
	s_andn2_saveexec_b64 s[28:29], s[28:29]
	s_cbranch_execz .LBB0_455
	s_mov_b64 s[28:29], exec
	v_mov_b32_e32 v5, 0x2000c
	ds_read_b32 v5, v5
	s_waitcnt lgkmcnt(0)
	v_readfirstlane_b32 s4, v5
	s_cmp_eq_u32 s4, 0
	s_cbranch_scc1 .Lsynco_local
	buffer_wbl2 sc1
	s_waitcnt lgkmcnt(0)
	s_waitcnt vmcnt(0)
	v_mbcnt_lo_u32_b32 v0, s28, 0
	v_mbcnt_hi_u32_b32 v0, s29, v0
	v_cmp_eq_u32_e32 vcc, 0, v0
	s_and_saveexec_b64 s[38:39], vcc
	s_cbranch_execz .LBB0_438
	s_bcnt1_i32_b64 s28, s[28:29]
	v_readlane_b32 s4, v253, 24
	v_mov_b32_e32 v3, s28
	v_readlane_b32 s5, v253, 25
	s_nop 4
	global_atomic_add v3, v1, v3, s[4:5] sc0

; __device__ __forceinline__ unsigned xb_add(unsigned* p, unsigned v) { return __hip_atomic_fetch_add(p, v, __ATOMIC_RELAXED, __HIP_MEMORY_SCOPE_AGENT); }
; __device__ __forceinline__ void xcd_barrier(const XcdBarrier& b) {
;     ...
;         const unsigned old = xb_add(&bar[XB_XSUB(b.x)], 1u);
;         const unsigned gen = old / nloc;
;         if (old + 1u == (gen + 1u) * nloc) {
.Lsynco_local:
	s_mov_b64 s[28:29], exec
	v_mbcnt_lo_u32_b32 v0, s28, 0
	v_mbcnt_hi_u32_b32 v0, s29, v0
	v_cmp_eq_u32_e32 vcc, 0, v0
	s_waitcnt vmcnt(0)
	s_and_saveexec_b64 s[38:39], vcc
	s_cbranch_execz .LBB0_454
	s_bcnt1_i32_b64 s28, s[28:29]
	v_readlane_b32 s4, v253, 22
	v_mov_b32_e32 v0, s28
	v_readlane_b32 s5, v253, 23
	s_nop 4
	global_atomic_add v1, v0, s[4:5]

; #define LAS __attribute__((address_space(3)))
; #define GSYNC() do { _Pragma("unroll 1") for (int sy_ = 0; sy_ < PROBE_SYNCREP; ++sy_) xcd_barrier(xbar); } while (0)
; __global__ void __launch_bounds__(NTHR, 2) mega_fwd(Args a) {
;     ...
;             GSYNC();
;             { pg8::Gemm g{HB, wl + (f ? W_D2 : W_D1), T, D, FF}; pg8::StaticOrder S; S.init(T, D, G, bx); pg8::EpiRes E{XB, SS, 0.5f, (LAS float*)(lds + 131072 + 256)};
.LBB0_657:
	s_or_b64 exec, exec, s[0:1]
	v_readlane_b32 s4, v254, 51
	v_readlane_b32 s5, v255, 10
	s_or_b32 s4, s4, s5
	s_cmp_lg_u32 s4, 0
	s_cbranch_scc1 .Lfb_skip
	s_and_saveexec_b64 s[0:1], s[80:81]
	s_cbranch_execz .Lfb_done
	v_mov_b32_e32 v0, 0x3e00
	global_load_dword v2, v0, s[50:51] sc1
	v_mov_b32_e32 v0, 0x2000c
	s_waitcnt vmcnt(0)
	ds_write_b32 v0, v2

; #define PG8_STAGE(bufoff, gbase, voff) do { _Pragma("unroll") for (int _i = 0; _i < 2; ++_i) \
;         __builtin_amdgcn_global_load_lds((const unsigned*)((const char*)(gbase) + (voff)[_i]), (PG8_LAS unsigned*)(lds + (bufoff) + ldsw + _i * 8192), 16, 0, 0); } while (0)
; #define PG8_BAR __builtin_amdgcn_s_barrier()
; template <class Epi, class Sched, bool ALIGN_EPI = false, bool SP2 = false>
; __device__ __forceinline__ void gemm_phase(PG8_LAS unsigned char* lds, const Gemm g, const Sched& S, const Epi& E) {
;     ...
;     const int tid = tid_, wid = __builtin_amdgcn_readfirstlane(tid >> 6), lane = tid & 63, wr = wid >> 2, wc = wid & 3, fr = lane & 15, fq = lane >> 4;
;     const int K = g.K, nt = K / BK;
;     unsigned voffA[2], voffB[2];
; #pragma unroll
;     for (int i = 0; i < 2; ++i) { int R, C; stage_rc(tid * 16 + i * 8192, R, C); const int Rb = Epi::PERM ? ((R & ~31) + perm32(R & 31)) : R;
;         voffA[i] = (unsigned)(R * K + C) * 2u; voffB[i] = (unsigned)(Rb * K + C) * 2u; }
;     const size_t kstep = (size_t)(BK * 2);
;     const size_t hstep = (size_t)HALF * K * 2;
;     const size_t tstep = 2 * hstep;
;     const unsigned ldsw = (unsigned)wid * 1024u;
;     const int aoff = lds_byte(wr * 64 + fr, fq * 8), boff = lds_byte(wc * 32 + fr, fq * 8);
;     ...
;     const char* cA = (const char*)g.A + (size_t)cur.pm * tstep; const char* cB = (const char*)g.Bt + (size_t)cur.pn * tstep;
;     S.a_ready(cur);
;     if constexpr (SP2) {
;         PG8_STAGE(PG8_SB(0, 0), cB, voffB); PG8_STAGE(PG8_SB(0, 1), cB + hstep, voffB); PG8_STAGE(PG8_SA(0, 0), cA, voffA); PG8_STAGE(PG8_SA(0, 1), cA + hstep, voffA);
;         if (wr == 1) PG8_BAR;
.Lfb_skip:
	v_readlane_b32 s4, v253, 37
	v_mov_b32_e32 v14, v226
	v_readlane_b32 s5, v253, 38
	s_xor_b64 s[0:1], s[8:9], -1
	s_waitcnt lgkmcnt(0)
	s_barrier
	s_and_b64 vcc, exec, s[4:5]
	v_readfirstlane_b32 s28, v14
	s_cbranch_vccz .LBB0_699
	v_lshlrev_b32_e32 v0, 4, v14
	v_add_u32_e32 v2, 0x2000, v0
	v_ashrrev_i32_e32 v3, 31, v2
	v_lshrrev_b32_e32 v3, 22, v3
	v_add_u32_e32 v3, v2, v3
	v_ashrrev_i32_e32 v6, 10, v3
	v_mul_i32_i24_e32 v3, 0x400, v6
	v_sub_u32_e32 v2, v2, v3
	v_lshrrev_b32_e32 v3, 4, v2
	v_bitop3_b32 v2, v3, v2, 32 bitop3:0x6c
	v_ashrrev_i32_e32 v3, 31, v2
	v_lshrrev_b32_e32 v3, 26, v3
	v_add_u32_e32 v3, v2, v3
	v_lshlrev_b32_e32 v4, 3, v6
	v_ashrrev_i32_e32 v7, 6, v3
	v_and_b32_e32 v4, -16, v4
	v_add_u32_e32 v4, v7, v4
	s_and_b64 s[38:39], s[8:9], exec
	s_mov_b32 s29, 0x2100000
	v_and_b32_e32 v5, 3, v7
	s_mov_b32 s5, 0xffffe0
	v_lshrrev_b32_e32 v8, 2, v4
	v_lshlrev_b32_e32 v9, 1, v4
	v_and_b32_e32 v3, 0xc0, v3
	s_cselect_b32 s29, 0xb00000, s29
	v_readlane_b32 s4, v254, 49
	v_and_or_b32 v5, v4, s5, v5
	v_and_b32_e32 v8, 4, v8
	v_and_b32_e32 v9, 24, v9
	v_sub_u32_e32 v2, v2, v3
	s_add_u32 s59, s4, s29
	v_readlane_b32 s4, v254, 50
	v_or3_b32 v5, v5, v8, v9
	v_lshlrev_b32_e32 v8, 5, v6
	v_ashrrev_i16_sdwa v2, v230, sext(v2) dst_sel:DWORD dst_unused:UNUSED_PAD src0_sel:DWORD src1_sel:BYTE_0
	s_addc_u32 s60, s4, 0
	v_and_b32_e32 v8, 32, v8
	v_bfe_i32 v9, v2, 0, 16
	s_movk_i32 s4, 0xb00
	v_mul_u32_u24_e32 v5, 0xb00, v5
	v_add_u32_e32 v2, v8, v9
	v_mul_lo_u32 v3, v4, s4
	v_add_lshl_u32 v200, v5, v2, 1
	v_add_lshl_u32 v202, v2, v3, 1
	v_bfe_i32 v2, v14, 27, 1
	v_lshrrev_b32_e32 v2, 22, v2
	v_add_u32_e32 v2, v0, v2
	v_and_b32_e32 v2, 0xfffffc00, v2
	v_sub_u32_e32 v0, v0, v2
	v_lshrrev_b32_e32 v2, 4, v0
	v_ashrrev_i32_e32 v3, 31, v14
	v_bitop3_b32 v0, v2, v0, 32 bitop3:0x6c
	v_lshrrev_b32_e32 v3, 26, v3
	v_ashrrev_i32_e32 v2, 31, v0
	v_add_u32_e32 v3, v14, v3
	v_lshrrev_b32_e32 v2, 26, v2
	v_ashrrev_i32_e32 v11, 6, v3
	v_add_u32_e32 v2, v0, v2
	v_lshlrev_b32_e32 v3, 3, v11
	v_ashrrev_i32_e32 v10, 6, v2
	v_and_b32_e32 v3, -16, v3
	v_add_u32_e32 v3, v10, v3
	v_and_b32_e32 v4, 3, v10
	v_lshrrev_b32_e32 v5, 2, v3
	v_lshlrev_b32_e32 v12, 1, v3
	v_and_b32_e32 v2, 0xc0, v2
	s_ashr_i32 s38, s28, 6
	v_and_or_b32 v4, v3, s5, v4
	v_and_b32_e32 v5, 4, v5
	v_and_b32_e32 v12, 24, v12
	v_sub_u32_e32 v0, v0, v2
	v_mul_lo_u32 v3, v3, s4
	v_readlane_b32 s4, v253, 62
	s_ashr_i32 s29, s28, 8
	s_lshl_b32 s61, s38, 10
	v_or3_b32 v4, v4, v5, v12
	v_lshlrev_b32_e32 v5, 5, v11
	v_ashrrev_i16_sdwa v0, v230, sext(v0) dst_sel:DWORD dst_unused:UNUSED_PAD src0_sel:DWORD src1_sel:BYTE_0
	s_mul_i32 s39, s4, 0x160000
	v_and_b32_e32 v12, 32, v5
	v_bfe_i32 v13, v0, 0, 16
	s_add_u32 s92, s59, s39
	s_mul_hi_i32 s39, s4, 0x160000
	v_mul_u32_u24_e32 v4, 0xb00, v4
	v_add_u32_e32 v2, v12, v13
	s_addc_u32 s93, s60, s39
	s_add_i32 s70, s61, 0
	v_add_lshl_u32 v0, v4, v2, 1
	s_add_i32 m0, s70, 0x10000
	v_readlane_b32 s4, v254, 18
	global_load_lds_dwordx4 v0, s[92:93]
	s_add_i32 m0, s70, 0x12000
	s_add_u32 s40, s92, 0xb0000
	global_load_lds_dwordx4 v200, s[92:93]
	s_addc_u32 s41, s93, 0
	s_add_i32 m0, s70, 0x14000
	v_add_lshl_u32 v204, v2, v3, 1
	global_load_lds_dwordx4 v0, s[40:41]
	s_add_i32 m0, s70, 0x16000
	v_readlane_b32 s5, v254, 19
	global_load_lds_dwordx4 v200, s[40:41]
	s_mov_b32 m0, s70
	s_add_i32 s71, s70, 0x2000
	s_add_i32 s72, s70, 0x4000
	s_nop 0
	global_load_lds_dwordx4 v204, s[4:5]
	s_mov_b32 m0, s71
	s_add_i32 s73, s70, 0x6000
	global_load_lds_dwordx4 v202, s[4:5]
	v_readlane_b32 s4, v254, 20
	s_mov_b32 m0, s72
	v_readlane_b32 s5, v254, 21
	v_mov_b32_e32 v201, v1
	s_cmp_eq_u32 s29, 1
	v_lshl_add_u64 v[2:3], s[92:93], 0, v[0:1]
	s_cselect_b64 s[44:45], -1, 0
	s_cmp_lg_u32 s29, 1
	global_load_lds_dwordx4 v204, s[4:5]
	s_mov_b32 m0, s73
	v_lshl_add_u64 v[4:5], s[92:93], 0, v[200:201]
	global_load_lds_dwordx4 v202, s[4:5]
	s_cbranch_scc1 .LBB0_660
	s_barrier

; __device__ __forceinline__ unsigned xb_ld(unsigned* p)              { return __hip_atomic_load(p, __ATOMIC_RELAXED, __HIP_MEMORY_SCOPE_AGENT); }
; __device__ __forceinline__ unsigned xb_add(unsigned* p, unsigned v) { return __hip_atomic_fetch_add(p, v, __ATOMIC_RELAXED, __HIP_MEMORY_SCOPE_AGENT); }
; #define XB_SPIN(cond, bar) do { unsigned _sp = 0; while (cond) { __builtin_amdgcn_s_sleep(1); \
;     if ((++_sp & 255u) == 0u) { if (xb_ld(&(bar)[XB_TMO])) break; if (_sp > XB_SPIN_CAP) { atomicAdd(&(bar)[XB_TMO], 1u); break; } } } } while (0)
; #define GSYNC() do { _Pragma("unroll 1") for (int sy_ = 0; sy_ < PROBE_SYNCREP; ++sy_) xcd_barrier(xbar); } while (0)
; __device__ __forceinline__ void xcd_barrier(const XcdBarrier& b) {
;     asm volatile("s_waitcnt vmcnt(0)" ::: "memory");
;     __syncthreads();
;     if (threadIdx.x == 0) {
;         unsigned* bar = b.bar;
;         __builtin_amdgcn_s_waitcnt(0);
;         unsigned nloc = b.st[0], nx = b.st[1];
;         if (nloc == 0u) { xcd_barrier_complete(bar, b.x, nloc, nx); b.st[0] = nloc; b.st[1] = nx; }
;         const unsigned old = xb_add(&bar[XB_XSUB(b.x)], 1u);
;         const unsigned gen = old / nloc;
;         if (old + 1u == (gen + 1u) * nloc) {
;             __builtin_amdgcn_fence(__ATOMIC_RELEASE, "agent");
;             asm volatile("s_waitcnt vmcnt(0)" ::: "memory");
;             const unsigned og = xb_add(&bar[XB_TOP], 1u);
;             const unsigned tg = og / nx;
;             if (og + 1u == (tg + 1u) * nx) xb_add(&bar[XB_TOPGEN], 1u);
;             else XB_SPIN(xb_ld(&bar[XB_TOPGEN]) == tg, bar);
;             __builtin_amdgcn_fence(__ATOMIC_ACQUIRE, "agent");
;             xb_add(&bar[XB_XGEN(b.x)], 1u);
;             asm volatile("s_waitcnt vmcnt(0)" ::: "memory");
;         } else {
;             XB_SPIN(xb_ld(&bar[XB_XGEN(b.x)]) == gen, bar);
;             __builtin_amdgcn_fence(__ATOMIC_ACQUIRE, "agent");
;             asm volatile("s_waitcnt vmcnt(0)" ::: "memory");
;         }
;     }
;     __syncthreads();
; }
; __global__ void __launch_bounds__(NTHR, 2) mega_fwd(Args a) {
;     ...
;             GSYNC();
.LBB0_732:
	s_mov_b64 s[28:29], exec
	v_mov_b32_e32 v5, 0x2000c
	ds_read_b32 v5, v5
	s_waitcnt lgkmcnt(0)
	v_readfirstlane_b32 s4, v5
	s_cmp_lg_u32 s4, 0
	s_cbranch_scc1 .Lsyncd_global
	v_readlane_b32 s4, v254, 51
	v_readlane_b32 s5, v255, 10
	s_and_b32 s5, s5, 4
	s_add_i32 s4, s4, s5
	s_cmp_eq_u32 s4, 7
	s_cbranch_scc0 .Lsyncd_local
.Lsyncd_global:
	buffer_wbl2 sc1
	s_waitcnt lgkmcnt(0)
	s_waitcnt vmcnt(0)
	v_mbcnt_lo_u32_b32 v0, s28, 0
	v_mbcnt_hi_u32_b32 v0, s29, v0
	v_cmp_eq_u32_e32 vcc, 0, v0
	s_and_saveexec_b64 s[40:41], vcc
	s_cbranch_execz .LBB0_734
	s_bcnt1_i32_b64 s28, s[28:29]
	v_readlane_b32 s4, v253, 24
	v_mov_b32_e32 v3, s28
	v_readlane_b32 s5, v253, 25
	s_nop 4
	global_atomic_add v3, v1, v3, s[4:5] sc0
